# weight transposes: all 64 row loads of a 64x64 tile in flight with counted waits instead of 8 serial round trips
# speedup vs baseline: 1.0200x; 1.0071x over previous
.LBB0_30:
	s_or_b64 exec, exec, s[22:23]
	s_lshl_b32 s26, s30, 6
	s_ashr_i32 s27, s26, 31
	s_mul_i32 s22, s18, s27
	s_mul_hi_u32 s23, s18, s26
	s_add_i32 s22, s23, s22
	s_mul_i32 s23, s19, s26
	s_add_i32 s23, s22, s23
	s_mul_i32 s22, s18, s26
	v_lshl_add_u64 v[24:25], s[22:23], 2, v[24:25]
	v_max_i32_e32 v0, 0, v26
	v_lshl_add_u64 v[24:25], v[0:1], 2, v[24:25]
	v_ashrrev_i32_e32 v30, 31, v23
	v_mad_u64_u32 v[32:33], s[24:25], s20, v23, 0
	v_mul_lo_u32 v31, s21, v23
	v_mul_lo_u32 v30, s20, v30
	v_add3_u32 v33, v33, v30, v31
	v_lshl_add_u64 v[20:21], v[32:33], 1, v[20:21]
	v_lshl_add_u64 v[20:21], s[26:27], 1, v[20:21]
	s_lshl_b64 s[24:25], s[18:19], 2
	v_cmp_gt_i32_e32 vcc, 0, v26
	s_add_i32 s29, s29, s38
	global_load_dword v64, v[24:25], off
	v_lshl_add_u64 v[24:25], v[24:25], 0, s[24:25]
	global_load_dword v65, v[24:25], off
	v_lshl_add_u64 v[24:25], v[24:25], 0, s[24:25]
	global_load_dword v66, v[24:25], off
	v_lshl_add_u64 v[24:25], v[24:25], 0, s[24:25]
	global_load_dword v67, v[24:25], off
	v_lshl_add_u64 v[24:25], v[24:25], 0, s[24:25]
	global_load_dword v68, v[24:25], off
	v_lshl_add_u64 v[24:25], v[24:25], 0, s[24:25]
	global_load_dword v69, v[24:25], off
	v_lshl_add_u64 v[24:25], v[24:25], 0, s[24:25]
	global_load_dword v70, v[24:25], off
	v_lshl_add_u64 v[24:25], v[24:25], 0, s[24:25]
	global_load_dword v71, v[24:25], off
	v_lshl_add_u64 v[24:25], v[24:25], 0, s[24:25]
	global_load_dword v72, v[24:25], off
	v_lshl_add_u64 v[24:25], v[24:25], 0, s[24:25]
	global_load_dword v73, v[24:25], off
	v_lshl_add_u64 v[24:25], v[24:25], 0, s[24:25]
	global_load_dword v74, v[24:25], off
	v_lshl_add_u64 v[24:25], v[24:25], 0, s[24:25]
	global_load_dword v75, v[24:25], off
	v_lshl_add_u64 v[24:25], v[24:25], 0, s[24:25]
	global_load_dword v76, v[24:25], off
	v_lshl_add_u64 v[24:25], v[24:25], 0, s[24:25]
	global_load_dword v77, v[24:25], off
	v_lshl_add_u64 v[24:25], v[24:25], 0, s[24:25]
	global_load_dword v78, v[24:25], off
	v_lshl_add_u64 v[24:25], v[24:25], 0, s[24:25]
	global_load_dword v79, v[24:25], off
	v_lshl_add_u64 v[24:25], v[24:25], 0, s[24:25]
	global_load_dword v80, v[24:25], off
	v_lshl_add_u64 v[24:25], v[24:25], 0, s[24:25]
	global_load_dword v81, v[24:25], off
	v_lshl_add_u64 v[24:25], v[24:25], 0, s[24:25]
	global_load_dword v82, v[24:25], off
	v_lshl_add_u64 v[24:25], v[24:25], 0, s[24:25]
	global_load_dword v83, v[24:25], off
	v_lshl_add_u64 v[24:25], v[24:25], 0, s[24:25]
	global_load_dword v84, v[24:25], off
	v_lshl_add_u64 v[24:25], v[24:25], 0, s[24:25]
	global_load_dword v85, v[24:25], off
	v_lshl_add_u64 v[24:25], v[24:25], 0, s[24:25]
	global_load_dword v86, v[24:25], off
	v_lshl_add_u64 v[24:25], v[24:25], 0, s[24:25]
	global_load_dword v87, v[24:25], off
	v_lshl_add_u64 v[24:25], v[24:25], 0, s[24:25]
	global_load_dword v88, v[24:25], off
	v_lshl_add_u64 v[24:25], v[24:25], 0, s[24:25]
	global_load_dword v89, v[24:25], off
	v_lshl_add_u64 v[24:25], v[24:25], 0, s[24:25]
	global_load_dword v90, v[24:25], off
	v_lshl_add_u64 v[24:25], v[24:25], 0, s[24:25]
	global_load_dword v91, v[24:25], off
	v_lshl_add_u64 v[24:25], v[24:25], 0, s[24:25]
	global_load_dword v92, v[24:25], off
	v_lshl_add_u64 v[24:25], v[24:25], 0, s[24:25]
	global_load_dword v93, v[24:25], off
	v_lshl_add_u64 v[24:25], v[24:25], 0, s[24:25]
	global_load_dword v94, v[24:25], off
	v_lshl_add_u64 v[24:25], v[24:25], 0, s[24:25]
	global_load_dword v95, v[24:25], off
	v_lshl_add_u64 v[24:25], v[24:25], 0, s[24:25]
	global_load_dword v96, v[24:25], off
	v_lshl_add_u64 v[24:25], v[24:25], 0, s[24:25]
	global_load_dword v97, v[24:25], off
	v_lshl_add_u64 v[24:25], v[24:25], 0, s[24:25]
	global_load_dword v98, v[24:25], off
	v_lshl_add_u64 v[24:25], v[24:25], 0, s[24:25]
	global_load_dword v99, v[24:25], off
	v_lshl_add_u64 v[24:25], v[24:25], 0, s[24:25]
	global_load_dword v100, v[24:25], off
	v_lshl_add_u64 v[24:25], v[24:25], 0, s[24:25]
	global_load_dword v101, v[24:25], off
	v_lshl_add_u64 v[24:25], v[24:25], 0, s[24:25]
	global_load_dword v102, v[24:25], off
	v_lshl_add_u64 v[24:25], v[24:25], 0, s[24:25]
	global_load_dword v103, v[24:25], off
	v_lshl_add_u64 v[24:25], v[24:25], 0, s[24:25]
	global_load_dword v104, v[24:25], off
	v_lshl_add_u64 v[24:25], v[24:25], 0, s[24:25]
	global_load_dword v105, v[24:25], off
	v_lshl_add_u64 v[24:25], v[24:25], 0, s[24:25]
	global_load_dword v106, v[24:25], off
	v_lshl_add_u64 v[24:25], v[24:25], 0, s[24:25]
	global_load_dword v107, v[24:25], off
	v_lshl_add_u64 v[24:25], v[24:25], 0, s[24:25]
	global_load_dword v108, v[24:25], off
	v_lshl_add_u64 v[24:25], v[24:25], 0, s[24:25]
	global_load_dword v109, v[24:25], off
	v_lshl_add_u64 v[24:25], v[24:25], 0, s[24:25]
	global_load_dword v110, v[24:25], off
	v_lshl_add_u64 v[24:25], v[24:25], 0, s[24:25]
	global_load_dword v111, v[24:25], off
	v_lshl_add_u64 v[24:25], v[24:25], 0, s[24:25]
	global_load_dword v112, v[24:25], off
	v_lshl_add_u64 v[24:25], v[24:25], 0, s[24:25]
	global_load_dword v113, v[24:25], off
	v_lshl_add_u64 v[24:25], v[24:25], 0, s[24:25]
	global_load_dword v114, v[24:25], off
	v_lshl_add_u64 v[24:25], v[24:25], 0, s[24:25]
	global_load_dword v115, v[24:25], off
	v_lshl_add_u64 v[24:25], v[24:25], 0, s[24:25]
	global_load_dword v116, v[24:25], off
	v_lshl_add_u64 v[24:25], v[24:25], 0, s[24:25]
	global_load_dword v117, v[24:25], off
	v_lshl_add_u64 v[24:25], v[24:25], 0, s[24:25]
	global_load_dword v118, v[24:25], off
	v_lshl_add_u64 v[24:25], v[24:25], 0, s[24:25]
	global_load_dword v119, v[24:25], off
	v_lshl_add_u64 v[24:25], v[24:25], 0, s[24:25]
	global_load_dword v120, v[24:25], off
	v_lshl_add_u64 v[24:25], v[24:25], 0, s[24:25]
	global_load_dword v121, v[24:25], off
	v_lshl_add_u64 v[24:25], v[24:25], 0, s[24:25]
	global_load_dword v122, v[24:25], off
	v_lshl_add_u64 v[24:25], v[24:25], 0, s[24:25]
	global_load_dword v123, v[24:25], off
	v_lshl_add_u64 v[24:25], v[24:25], 0, s[24:25]
	global_load_dword v124, v[24:25], off
	v_lshl_add_u64 v[24:25], v[24:25], 0, s[24:25]
	global_load_dword v125, v[24:25], off
	v_lshl_add_u64 v[24:25], v[24:25], 0, s[24:25]
	global_load_dword v126, v[24:25], off
	v_lshl_add_u64 v[24:25], v[24:25], 0, s[24:25]
	global_load_dword v127, v[24:25], off
	s_waitcnt vmcnt(56)
	v_cvt_pk_bf16_f32 v64, v64, v65
	v_cvt_pk_bf16_f32 v65, v66, v67
	v_cvt_pk_bf16_f32 v66, v68, v69
	v_cvt_pk_bf16_f32 v67, v70, v71
	v_cndmask_b32_e64 v64, v64, 0, vcc
	v_cndmask_b32_e64 v65, v65, 0, vcc
	v_cndmask_b32_e64 v66, v66, 0, vcc
	v_cndmask_b32_e64 v67, v67, 0, vcc
	global_store_dwordx4 v[20:21], v[64:67], off
	s_waitcnt vmcnt(49)
	v_cvt_pk_bf16_f32 v72, v72, v73
	v_cvt_pk_bf16_f32 v73, v74, v75
	v_cvt_pk_bf16_f32 v74, v76, v77
	v_cvt_pk_bf16_f32 v75, v78, v79
	v_cndmask_b32_e64 v72, v72, 0, vcc
	v_cndmask_b32_e64 v73, v73, 0, vcc
	v_cndmask_b32_e64 v74, v74, 0, vcc
	v_cndmask_b32_e64 v75, v75, 0, vcc
	global_store_dwordx4 v[20:21], v[72:75], off offset:16
	s_waitcnt vmcnt(42)
	v_cvt_pk_bf16_f32 v80, v80, v81
	v_cvt_pk_bf16_f32 v81, v82, v83
	v_cvt_pk_bf16_f32 v82, v84, v85
	v_cvt_pk_bf16_f32 v83, v86, v87
	v_cndmask_b32_e64 v80, v80, 0, vcc
	v_cndmask_b32_e64 v81, v81, 0, vcc
	v_cndmask_b32_e64 v82, v82, 0, vcc
	v_cndmask_b32_e64 v83, v83, 0, vcc
	global_store_dwordx4 v[20:21], v[80:83], off offset:32
	s_waitcnt vmcnt(35)
	v_cvt_pk_bf16_f32 v88, v88, v89
	v_cvt_pk_bf16_f32 v89, v90, v91
	v_cvt_pk_bf16_f32 v90, v92, v93
	v_cvt_pk_bf16_f32 v91, v94, v95
	v_cndmask_b32_e64 v88, v88, 0, vcc
	v_cndmask_b32_e64 v89, v89, 0, vcc
	v_cndmask_b32_e64 v90, v90, 0, vcc
	v_cndmask_b32_e64 v91, v91, 0, vcc
	global_store_dwordx4 v[20:21], v[88:91], off offset:48
	s_waitcnt vmcnt(28)
	v_cvt_pk_bf16_f32 v96, v96, v97
	v_cvt_pk_bf16_f32 v97, v98, v99
	v_cvt_pk_bf16_f32 v98, v100, v101
	v_cvt_pk_bf16_f32 v99, v102, v103
	v_cndmask_b32_e64 v96, v96, 0, vcc
	v_cndmask_b32_e64 v97, v97, 0, vcc
	v_cndmask_b32_e64 v98, v98, 0, vcc
	v_cndmask_b32_e64 v99, v99, 0, vcc
	global_store_dwordx4 v[20:21], v[96:99], off offset:64
	s_waitcnt vmcnt(21)
	v_cvt_pk_bf16_f32 v104, v104, v105
	v_cvt_pk_bf16_f32 v105, v106, v107
	v_cvt_pk_bf16_f32 v106, v108, v109
	v_cvt_pk_bf16_f32 v107, v110, v111
	v_cndmask_b32_e64 v104, v104, 0, vcc
	v_cndmask_b32_e64 v105, v105, 0, vcc
	v_cndmask_b32_e64 v106, v106, 0, vcc
	v_cndmask_b32_e64 v107, v107, 0, vcc
	global_store_dwordx4 v[20:21], v[104:107], off offset:80
	s_waitcnt vmcnt(14)
	v_cvt_pk_bf16_f32 v112, v112, v113
	v_cvt_pk_bf16_f32 v113, v114, v115
	v_cvt_pk_bf16_f32 v114, v116, v117
	v_cvt_pk_bf16_f32 v115, v118, v119
	v_cndmask_b32_e64 v112, v112, 0, vcc
	v_cndmask_b32_e64 v113, v113, 0, vcc
	v_cndmask_b32_e64 v114, v114, 0, vcc
	v_cndmask_b32_e64 v115, v115, 0, vcc
	global_store_dwordx4 v[20:21], v[112:115], off offset:96
	s_waitcnt vmcnt(7)
	v_cvt_pk_bf16_f32 v120, v120, v121
	v_cvt_pk_bf16_f32 v121, v122, v123
	v_cvt_pk_bf16_f32 v122, v124, v125
	v_cvt_pk_bf16_f32 v123, v126, v127
	v_cndmask_b32_e64 v120, v120, 0, vcc
	v_cndmask_b32_e64 v121, v121, 0, vcc
	v_cndmask_b32_e64 v122, v122, 0, vcc
	v_cndmask_b32_e64 v123, v123, 0, vcc
	global_store_dwordx4 v[20:21], v[120:123], off offset:112
	s_cmpk_gt_i32 s29, 0x10c3
	s_cbranch_scc1 .LBB0_68
